# v81 + MLA loop: hazard nop between the m0 write and the last DMA replaced by an independent scalar op
# speedup vs baseline: 1.0001x; 1.0001x over previous
; #define SBAR() __builtin_amdgcn_sched_barrier(0)
; #define ATT_DMA_K(t) do { const bf16_t* kg_ = Kh + (size_t)(t) * 64 * LDK; LAS unsigned char* sb_ = lds + ((t) & 3) * KBUF; \
;     _Pragma("unroll") for (int i_ = 0; i_ < NKP; ++i_) __builtin_amdgcn_global_load_lds((const unsigned*)(kg_ + kgo[i_]), (LAS unsigned*)(sb_ + (wid + 8 * i_) * 1024), 16, 0, 0); } while (0)
; #define ATT_DMA_V(t, vs) do { const bf16_t* vg_ = Vh + (size_t)(t) * 64 * LDV; LAS unsigned char* sb_ = lds + V_OFF + (vs) * SHM_V; \
;     _Pragma("unroll") for (int i_ = 0; i_ < 2; ++i_) __builtin_amdgcn_global_load_lds((const unsigned*)(vg_ + vgo[i_]), (LAS unsigned*)(sb_ + (2 * wid + i_) * 1024), 16, 0, 0); } while (0)
; #define ATT_SEG(t) do { if constexpr (MODE != 0) { if (((t) == tL && tL > 0) || (t) == tR) { const float f_ = (t) == tR ? fR : fL; l_reg *= f_; \
;     _Pragma("unroll") for (int d = 0; d < 4; ++d) _Pragma("unroll") for (int r = 0; r < 16; ++r) o[d][r] *= f_; } } } while (0)
; #define ATT_BIAS(P, t, half) do { if constexpr (MODE != 0) { if ((t) >= tL && (t) < tR) { const LAS float* bp_ = bt + ((t) * 64 + (half) * 32 - qpos + 224 + 4 * hi);     \
;     _Pragma("unroll") for (int r = 0; r < 16; ++r) P[r] += bp_[(r & 3) + 8 * (r >> 2)]; } } } while (0)
; #define ATT_TOP(N) do { asm volatile("s_waitcnt vmcnt(%0)" :: "n"(N) : "memory"); __builtin_amdgcn_s_barrier(); asm volatile("" ::: "memory"); } while (0)
; template <int DQK, int MODE, int LDQ, int LDK, int LDV> ...
;     ...
;     f32x16 pA, pB; bf16x8 pa0, pa1;
;     int v0 = 0, v1 = 1, v2 = 2;
;     ATT_TOP(NKP + 2);
;     { bf16x8 kf[NDA]; k_reads<DQK, 0, NDA>(kf, lds, 0, r32, hi); ATT_LGKM0(); qk_mma<0, NDA>(pA, kf, qr);
;       if constexpr (ND0 > NDA) { bf16x8 kg[ND0 - NDA]; k_reads<DQK, NDA, ND0>(kg, lds, 0, r32, hi); ATT_LGKM0(); qk_mma<NDA, ND0>(pA, kg, qr); }
;       ATT_BIAS(pA, 0, 0); }
;     if (wid >= 4) __builtin_amdgcn_s_setprio(1);
;     for (int j = 0; j < NT; ++j) {
;         if (j + 2 < NT) ATT_TOP(NKP + 2); else ATT_TOP(0);
;         if (j + 3 < NT) ATT_DMA_K(j + 3);
;         if (j + 2 < NT) ATT_DMA_V(j + 2, v2);
;         ATT_SEG(j); SBAR();
;         ATT_STEP(pA, pB, 0, v0, true, 1, j);
;         ATT_STEP(pB, pA, 1, v0, (j + 1 < NT), 0, j + 1);
;         { const int t_ = v0; v0 = v1; v1 = v2; v2 = t_; }
;     }
.Lhw_mla_b_n1982:
	s_and_b32 s1, s43, 3
	s_mulk_i32 s1, 0x6000
	s_add_i32 s1, s49, s1
	s_setprio 0
	s_mov_b32 m0, s1
	s_mov_b32 s0, s5
	s_mov_b32 s5, s44
	s_mov_b32 s44, s4
	s_lshl_b32 s4, s4, 14
	global_load_lds_dwordx4 v136, s[34:35]
	s_add_i32 m0, s1, 0x2000
	s_add_i32 s4, s52, s4
	global_load_lds_dwordx4 v138, s[34:35]
	s_add_i32 m0, s1, 0x4000
	s_add_i32 s6, s4, 0x400
	global_load_lds_dwordx4 v140, s[34:35]
	s_mov_b32 m0, s4
	s_add_i32 s1, s43, -3
	global_load_lds_dwordx4 v144, s[34:35]
	s_mov_b32 m0, s6
	s_and_b32 s1, s1, 3
	global_load_lds_dwordx4 v142, s[34:35]
	s_mulk_i32 s1, 0x6000
	v_add_u32_e32 v246, s1, v158
	v_add_u32_e32 v250, v246, v151
	v_add_u32_e32 v251, v246, v149
	v_add_u32_e32 v252, v246, v148
	v_add_u32_e32 v253, v246, v147
	s_lshl_b32 s1, s0, 14
	ds_read_b128 v[190:193], v250 offset:12416
	ds_read_b128 v[194:197], v251 offset:12416
	ds_read_b128 v[174:177], v250 offset:12288
	ds_read_b128 v[178:181], v251 offset:12288
	ds_read_b128 v[182:185], v252 offset:12288
	ds_read_b128 v[186:189], v253 offset:12288
	v_add_u32_e32 v254, s1, v130
	ds_read_b64_tr_b16 v[198:199], v254 offset:0
	ds_read_b64_tr_b16 v[200:201], v254 offset:0x800
	ds_read_b64_tr_b16 v[202:203], v254 offset:0x1000
	ds_read_b64_tr_b16 v[204:205], v254 offset:0x1800
	ds_read_b64_tr_b16 v[206:207], v254 offset:0x200
	ds_read_b64_tr_b16 v[208:209], v254 offset:0xa00
	ds_read_b64_tr_b16 v[210:211], v254 offset:0x1200
	ds_read_b64_tr_b16 v[212:213], v254 offset:0x1a00
	ds_read_b64_tr_b16 v[214:215], v254 offset:0x400
	ds_read_b64_tr_b16 v[216:217], v254 offset:0xc00
	ds_read_b64_tr_b16 v[218:219], v254 offset:0x1400
	ds_read_b64_tr_b16 v[220:221], v254 offset:0x1c00
	ds_read_b64_tr_b16 v[222:223], v254 offset:0x600
	ds_read_b64_tr_b16 v[224:225], v254 offset:0xe00
	ds_read_b64_tr_b16 v[226:227], v254 offset:0x1600
	ds_read_b64_tr_b16 v[228:229], v254 offset:0x1e00
	s_setprio 1
	v_exp_f32_e32 v64, v64
	v_exp_f32_e32 v65, v65
	v_exp_f32_e32 v66, v66
	v_exp_f32_e32 v67, v67
	v_exp_f32_e32 v68, v68
	v_exp_f32_e32 v69, v69
	v_add_f32_e32 v230, v65, v64
	v_exp_f32_e32 v70, v70
	v_add_f32_e32 v230, v66, v230
	v_exp_f32_e32 v71, v71
	v_add_f32_e32 v230, v67, v230
	v_exp_f32_e32 v72, v72
	v_add_f32_e32 v230, v68, v230
	v_exp_f32_e32 v73, v73
	v_add_f32_e32 v230, v69, v230
	v_exp_f32_e32 v74, v74
	v_add_f32_e32 v230, v70, v230
	v_exp_f32_e32 v75, v75
	v_add_f32_e32 v230, v71, v230
	v_exp_f32_e32 v76, v76
	v_add_f32_e32 v230, v72, v230
	v_exp_f32_e32 v77, v77
	v_add_f32_e32 v230, v73, v230
	v_exp_f32_e32 v78, v78
	v_add_f32_e32 v230, v74, v230
	v_exp_f32_e32 v79, v79
	v_add_f32_e32 v230, v75, v230
	v_add_f32_e32 v230, v76, v230
	v_add_f32_e32 v230, v77, v230
	v_add_f32_e32 v230, v78, v230
	v_add_f32_e32 v230, v79, v230
	v_add_f32_e32 v173, v173, v230
	v_cvt_pk_bf16_f32 v64, v64, v65
	v_cvt_pk_bf16_f32 v65, v66, v67
	v_cvt_pk_bf16_f32 v66, v68, v69
	v_cvt_pk_bf16_f32 v67, v70, v71
	v_cvt_pk_bf16_f32 v68, v72, v73
	v_cvt_pk_bf16_f32 v69, v74, v75
	v_cvt_pk_bf16_f32 v70, v76, v77
	v_cvt_pk_bf16_f32 v71, v78, v79
	s_waitcnt lgkmcnt(0)
	ds_read_b128 v[230:233], v252 offset:12416
	ds_read_b128 v[234:237], v253 offset:12416
	ds_read_b128 v[238:241], v250 offset:12544
	ds_read_b128 v[242:245], v251 offset:12544
	ds_read_b128 v[246:249], v252 offset:12544
	ds_read_b128 v[250:253], v253 offset:12544
	s_setprio 2
	v_mfma_f32_32x32x16_bf16 v[48:63], v[64:67], v[198:201], v[48:63]
	v_mfma_f32_32x32x16_bf16 v[32:47], v[64:67], v[206:209], v[32:47]
	v_mfma_f32_32x32x16_bf16 v[16:31], v[64:67], v[214:217], v[16:31]
	v_mfma_f32_32x32x16_bf16 v[0:15], v[64:67], v[222:225], v[0:15]
	v_mfma_f32_32x32x16_bf16 v[48:63], v[68:71], v[202:205], v[48:63]
	v_mfma_f32_32x32x16_bf16 v[32:47], v[68:71], v[210:213], v[32:47]
	v_mfma_f32_32x32x16_bf16 v[16:31], v[68:71], v[218:221], v[16:31]
	v_mfma_f32_32x32x16_bf16 v[0:15], v[68:71], v[226:229], v[0:15]
	s_waitcnt lgkmcnt(0)
	v_mfma_f32_32x32x16_bf16 v[64:79], v[174:177], v[80:83], 0
	v_mfma_f32_32x32x16_bf16 v[64:79], v[178:181], v[84:87], v[64:79]
	v_mfma_f32_32x32x16_bf16 v[64:79], v[182:185], v[88:91], v[64:79]
	v_mfma_f32_32x32x16_bf16 v[64:79], v[186:189], v[92:95], v[64:79]
	v_mfma_f32_32x32x16_bf16 v[64:79], v[190:193], v[96:99], v[64:79]
	v_mfma_f32_32x32x16_bf16 v[64:79], v[194:197], v[100:103], v[64:79]
	v_mfma_f32_32x32x16_bf16 v[64:79], v[230:233], v[104:107], v[64:79]
	v_mfma_f32_32x32x16_bf16 v[64:79], v[234:237], v[108:111], v[64:79]
	v_mfma_f32_32x32x16_bf16 v[64:79], v[238:241], v[112:115], v[64:79]
	v_mfma_f32_32x32x16_bf16 v[64:79], v[242:245], v[116:119], v[64:79]
	v_mfma_f32_32x32x16_bf16 v[64:79], v[246:249], v[120:123], v[64:79]
	v_mfma_f32_32x32x16_bf16 v[64:79], v[250:253], v[124:127], v[64:79]
	s_setprio 0
	s_add_i32 s4, s43, -2
	s_and_b32 s4, s4, 3
	s_mulk_i32 s4, 0x6000
	v_add_u32_e32 v246, s4, v158
	v_add_u32_e32 v250, v246, v151
	v_add_u32_e32 v251, v246, v149
	v_add_u32_e32 v252, v246, v148
	v_add_u32_e32 v253, v246, v147
	ds_read_b128 v[190:193], v250 offset:128
	ds_read_b128 v[194:197], v251 offset:128
	ds_read_b128 v[174:177], v250
	ds_read_b128 v[178:181], v251
	ds_read_b128 v[182:185], v252
	ds_read_b128 v[186:189], v253
	ds_read_b64_tr_b16 v[198:199], v254 offset:0x2000
	ds_read_b64_tr_b16 v[200:201], v254 offset:0x2800
	ds_read_b64_tr_b16 v[202:203], v254 offset:0x3000
	ds_read_b64_tr_b16 v[204:205], v254 offset:0x3800
	ds_read_b64_tr_b16 v[206:207], v254 offset:0x2200
	ds_read_b64_tr_b16 v[208:209], v254 offset:0x2a00
	ds_read_b64_tr_b16 v[210:211], v254 offset:0x3200
	ds_read_b64_tr_b16 v[212:213], v254 offset:0x3a00
	ds_read_b64_tr_b16 v[214:215], v254 offset:0x2400
	ds_read_b64_tr_b16 v[216:217], v254 offset:0x2c00
; #define SBAR() __builtin_amdgcn_sched_barrier(0)
; #define ATT_DMA_K(t) do { const bf16_t* kg_ = Kh + (size_t)(t) * 64 * LDK; LAS unsigned char* sb_ = lds + ((t) & 3) * KBUF; \
;     _Pragma("unroll") for (int i_ = 0; i_ < NKP; ++i_) __builtin_amdgcn_global_load_lds((const unsigned*)(kg_ + kgo[i_]), (LAS unsigned*)(sb_ + (wid + 8 * i_) * 1024), 16, 0, 0); } while (0)
; #define ATT_DMA_V(t, vs) do { const bf16_t* vg_ = Vh + (size_t)(t) * 64 * LDV; LAS unsigned char* sb_ = lds + V_OFF + (vs) * SHM_V; \
;     _Pragma("unroll") for (int i_ = 0; i_ < 2; ++i_) __builtin_amdgcn_global_load_lds((const unsigned*)(vg_ + vgo[i_]), (LAS unsigned*)(sb_ + (2 * wid + i_) * 1024), 16, 0, 0); } while (0)
; #define ATT_SEG(t) do { if constexpr (MODE != 0) { if (((t) == tL && tL > 0) || (t) == tR) { const float f_ = (t) == tR ? fR : fL; l_reg *= f_; \
;     _Pragma("unroll") for (int d = 0; d < 4; ++d) _Pragma("unroll") for (int r = 0; r < 16; ++r) o[d][r] *= f_; } } } while (0)
; #define ATT_BIAS(P, t, half) do { if constexpr (MODE != 0) { if ((t) >= tL && (t) < tR) { const LAS float* bp_ = bt + ((t) * 64 + (half) * 32 - qpos + 224 + 4 * hi);     \
;     _Pragma("unroll") for (int r = 0; r < 16; ++r) P[r] += bp_[(r & 3) + 8 * (r >> 2)]; } } } while (0)
; #define ATT_TOP(N) do { asm volatile("s_waitcnt vmcnt(%0)" :: "n"(N) : "memory"); __builtin_amdgcn_s_barrier(); asm volatile("" ::: "memory"); } while (0)
; template <int DQK, int MODE, int LDQ, int LDK, int LDV> ...
;     ...
;     f32x16 pA, pB; bf16x8 pa0, pa1;
;     int v0 = 0, v1 = 1, v2 = 2;
;     ATT_TOP(NKP + 2);
;     { bf16x8 kf[NDA]; k_reads<DQK, 0, NDA>(kf, lds, 0, r32, hi); ATT_LGKM0(); qk_mma<0, NDA>(pA, kf, qr);
;       if constexpr (ND0 > NDA) { bf16x8 kg[ND0 - NDA]; k_reads<DQK, NDA, ND0>(kg, lds, 0, r32, hi); ATT_LGKM0(); qk_mma<NDA, ND0>(pA, kg, qr); }
;       ATT_BIAS(pA, 0, 0); }
;     if (wid >= 4) __builtin_amdgcn_s_setprio(1);
;     for (int j = 0; j < NT; ++j) {
;         if (j + 2 < NT) ATT_TOP(NKP + 2); else ATT_TOP(0);
;         if (j + 3 < NT) ATT_DMA_K(j + 3);
;         if (j + 2 < NT) ATT_DMA_V(j + 2, v2);
;         ATT_SEG(j); SBAR();
;         ATT_STEP(pA, pB, 0, v0, true, 1, j);
;         ATT_STEP(pB, pA, 1, v0, (j + 1 < NT), 0, j + 1);
;         { const int t_ = v0; v0 = v1; v1 = v2; v2 = t_; }
;     }
	ds_read_b64_tr_b16 v[218:219], v254 offset:0x3400
	ds_read_b64_tr_b16 v[220:221], v254 offset:0x3c00
	ds_read_b64_tr_b16 v[222:223], v254 offset:0x2600
	ds_read_b64_tr_b16 v[224:225], v254 offset:0x2e00
	ds_read_b64_tr_b16 v[226:227], v254 offset:0x3600
	ds_read_b64_tr_b16 v[228:229], v254 offset:0x3e00
	s_setprio 1
	v_exp_f32_e32 v64, v64
	v_exp_f32_e32 v65, v65
	v_exp_f32_e32 v66, v66
	v_exp_f32_e32 v67, v67
	v_exp_f32_e32 v68, v68
	v_exp_f32_e32 v69, v69
	v_add_f32_e32 v230, v65, v64
	v_exp_f32_e32 v70, v70
	v_add_f32_e32 v230, v66, v230
	v_exp_f32_e32 v71, v71
	v_add_f32_e32 v230, v67, v230
	v_exp_f32_e32 v72, v72
	v_add_f32_e32 v230, v68, v230
	v_exp_f32_e32 v73, v73
	v_add_f32_e32 v230, v69, v230
	v_exp_f32_e32 v74, v74
	v_add_f32_e32 v230, v70, v230
	v_exp_f32_e32 v75, v75
	v_add_f32_e32 v230, v71, v230
	v_exp_f32_e32 v76, v76
	v_add_f32_e32 v230, v72, v230
	v_exp_f32_e32 v77, v77
	v_add_f32_e32 v230, v73, v230
	v_exp_f32_e32 v78, v78
	v_add_f32_e32 v230, v74, v230
	v_exp_f32_e32 v79, v79
	v_add_f32_e32 v230, v75, v230
	v_add_f32_e32 v230, v76, v230
	v_add_f32_e32 v230, v77, v230
	v_add_f32_e32 v230, v78, v230
	v_add_f32_e32 v230, v79, v230
	v_add_f32_e32 v173, v173, v230
	v_cvt_pk_bf16_f32 v64, v64, v65
	v_cvt_pk_bf16_f32 v65, v66, v67
	v_cvt_pk_bf16_f32 v66, v68, v69
	v_cvt_pk_bf16_f32 v67, v70, v71
	v_cvt_pk_bf16_f32 v68, v72, v73
	v_cvt_pk_bf16_f32 v69, v74, v75
	v_cvt_pk_bf16_f32 v70, v76, v77
	v_cvt_pk_bf16_f32 v71, v78, v79
	s_waitcnt lgkmcnt(0)
	ds_read_b128 v[230:233], v252 offset:128
	ds_read_b128 v[234:237], v253 offset:128
	ds_read_b128 v[238:241], v250 offset:256
	ds_read_b128 v[242:245], v251 offset:256
	ds_read_b128 v[246:249], v252 offset:256
	ds_read_b128 v[250:253], v253 offset:256
	s_setprio 2
	s_waitcnt vmcnt(5)
	s_barrier
	v_mfma_f32_32x32x16_bf16 v[48:63], v[64:67], v[198:201], v[48:63]
	v_mfma_f32_32x32x16_bf16 v[32:47], v[64:67], v[206:209], v[32:47]
	v_mfma_f32_32x32x16_bf16 v[16:31], v[64:67], v[214:217], v[16:31]
	v_mfma_f32_32x32x16_bf16 v[0:15], v[64:67], v[222:225], v[0:15]
	v_mfma_f32_32x32x16_bf16 v[48:63], v[68:71], v[202:205], v[48:63]
	v_mfma_f32_32x32x16_bf16 v[32:47], v[68:71], v[210:213], v[32:47]
	v_mfma_f32_32x32x16_bf16 v[16:31], v[68:71], v[218:221], v[16:31]
	v_mfma_f32_32x32x16_bf16 v[0:15], v[68:71], v[226:229], v[0:15]
	s_waitcnt lgkmcnt(0)
	v_mfma_f32_32x32x16_bf16 v[64:79], v[174:177], v[80:83], 0
	v_mfma_f32_32x32x16_bf16 v[64:79], v[178:181], v[84:87], v[64:79]
	v_mfma_f32_32x32x16_bf16 v[64:79], v[182:185], v[88:91], v[64:79]
	v_mfma_f32_32x32x16_bf16 v[64:79], v[186:189], v[92:95], v[64:79]
	v_mfma_f32_32x32x16_bf16 v[64:79], v[190:193], v[96:99], v[64:79]
	v_mfma_f32_32x32x16_bf16 v[64:79], v[194:197], v[100:103], v[64:79]
	v_mfma_f32_32x32x16_bf16 v[64:79], v[230:233], v[104:107], v[64:79]
	v_mfma_f32_32x32x16_bf16 v[64:79], v[234:237], v[108:111], v[64:79]
	v_mfma_f32_32x32x16_bf16 v[64:79], v[238:241], v[112:115], v[64:79]
	v_mfma_f32_32x32x16_bf16 v[64:79], v[242:245], v[116:119], v[64:79]
	v_mfma_f32_32x32x16_bf16 v[64:79], v[246:249], v[120:123], v[64:79]
	v_mfma_f32_32x32x16_bf16 v[64:79], v[250:253], v[124:127], v[64:79]
	s_add_i32 s43, s43, 1
	v_add_u32_e32 v136, s36, v136
	v_add_u32_e32 v138, s36, v138
	v_add_u32_e32 v140, s36, v140
	v_add_u32_e32 v142, s38, v142
	v_add_u32_e32 v144, s38, v144
	s_cmp_eq_u32 s43, 64
	s_mov_b32 s4, s0
	s_cbranch_scc0 .Lhw_mla_b_n1982
	s_branch .Lhw_mla_exit
.LBB0_1982:
	s_and_b32 s1, s43, 3
	s_mulk_i32 s1, 0x6000
	s_add_i32 s1, s49, s1
	s_waitcnt vmcnt(5)
	s_barrier
	s_setprio 0
	s_mov_b32 m0, s1
	s_mov_b32 s0, s5
	s_mov_b32 s5, s44
	s_mov_b32 s44, s4
	s_lshl_b32 s4, s4, 14
	global_load_lds_dwordx4 v136, s[34:35]
	s_add_i32 m0, s1, 0x2000
	s_add_i32 s4, s52, s4
	global_load_lds_dwordx4 v138, s[34:35]
	s_add_i32 m0, s1, 0x4000
	s_add_i32 s6, s4, 0x400
	global_load_lds_dwordx4 v140, s[34:35]
	s_mov_b32 m0, s4
	s_add_i32 s1, s43, -3
	global_load_lds_dwordx4 v144, s[34:35]
	s_mov_b32 m0, s6
	s_and_b32 s1, s1, 3
	global_load_lds_dwordx4 v142, s[34:35]
	s_mulk_i32 s1, 0x6000
	v_add_u32_e32 v246, s1, v158
	v_add_u32_e32 v250, v246, v151
	v_add_u32_e32 v251, v246, v149
	v_add_u32_e32 v252, v246, v148
	v_add_u32_e32 v253, v246, v147
	s_lshl_b32 s1, s0, 14
	ds_read_b128 v[190:193], v250 offset:12416
	ds_read_b128 v[194:197], v251 offset:12416
	ds_read_b128 v[174:177], v250 offset:12288
	ds_read_b128 v[178:181], v251 offset:12288
	ds_read_b128 v[182:185], v252 offset:12288
	ds_read_b128 v[186:189], v253 offset:12288
	v_add_u32_e32 v254, s1, v130
	ds_read_b64_tr_b16 v[198:199], v254 offset:0
	ds_read_b64_tr_b16 v[200:201], v254 offset:0x800
	ds_read_b64_tr_b16 v[202:203], v254 offset:0x1000
	ds_read_b64_tr_b16 v[204:205], v254 offset:0x1800
	ds_read_b64_tr_b16 v[206:207], v254 offset:0x200
	ds_read_b64_tr_b16 v[208:209], v254 offset:0xa00
	ds_read_b64_tr_b16 v[210:211], v254 offset:0x1200
	ds_read_b64_tr_b16 v[212:213], v254 offset:0x1a00
	ds_read_b64_tr_b16 v[214:215], v254 offset:0x400
	ds_read_b64_tr_b16 v[216:217], v254 offset:0xc00
	ds_read_b64_tr_b16 v[218:219], v254 offset:0x1400
	ds_read_b64_tr_b16 v[220:221], v254 offset:0x1c00
	ds_read_b64_tr_b16 v[222:223], v254 offset:0x600
	ds_read_b64_tr_b16 v[224:225], v254 offset:0xe00
	ds_read_b64_tr_b16 v[226:227], v254 offset:0x1600
	ds_read_b64_tr_b16 v[228:229], v254 offset:0x1e00
	s_setprio 1
	v_exp_f32_e32 v64, v64
	v_exp_f32_e32 v65, v65
	v_exp_f32_e32 v66, v66
	v_exp_f32_e32 v67, v67
	v_exp_f32_e32 v68, v68
	v_exp_f32_e32 v69, v69
	v_add_f32_e32 v230, v65, v64
	v_exp_f32_e32 v70, v70
	v_add_f32_e32 v230, v66, v230
	v_exp_f32_e32 v71, v71
	v_add_f32_e32 v230, v67, v230
	v_exp_f32_e32 v72, v72
	v_add_f32_e32 v230, v68, v230
	v_exp_f32_e32 v73, v73
	v_add_f32_e32 v230, v69, v230
	v_exp_f32_e32 v74, v74
	v_add_f32_e32 v230, v70, v230
	v_exp_f32_e32 v75, v75
	v_add_f32_e32 v230, v71, v230
	v_exp_f32_e32 v76, v76
	v_add_f32_e32 v230, v72, v230
	v_exp_f32_e32 v77, v77
	v_add_f32_e32 v230, v73, v230
	v_exp_f32_e32 v78, v78
	v_add_f32_e32 v230, v74, v230
	v_exp_f32_e32 v79, v79
	v_add_f32_e32 v230, v75, v230
	v_add_f32_e32 v230, v76, v230
	v_add_f32_e32 v230, v77, v230
	v_add_f32_e32 v230, v78, v230
	v_add_f32_e32 v230, v79, v230
	v_add_f32_e32 v173, v173, v230
	v_cvt_pk_bf16_f32 v64, v64, v65
	v_cvt_pk_bf16_f32 v65, v66, v67
	v_cvt_pk_bf16_f32 v66, v68, v69
	v_cvt_pk_bf16_f32 v67, v70, v71
	v_cvt_pk_bf16_f32 v68, v72, v73
	v_cvt_pk_bf16_f32 v69, v74, v75
	v_cvt_pk_bf16_f32 v70, v76, v77
	v_cvt_pk_bf16_f32 v71, v78, v79
	s_waitcnt lgkmcnt(0)
; #define SBAR() __builtin_amdgcn_sched_barrier(0)
; #define ATT_DMA_K(t) do { const bf16_t* kg_ = Kh + (size_t)(t) * 64 * LDK; LAS unsigned char* sb_ = lds + ((t) & 3) * KBUF; \
;     _Pragma("unroll") for (int i_ = 0; i_ < NKP; ++i_) __builtin_amdgcn_global_load_lds((const unsigned*)(kg_ + kgo[i_]), (LAS unsigned*)(sb_ + (wid + 8 * i_) * 1024), 16, 0, 0); } while (0)
; #define ATT_DMA_V(t, vs) do { const bf16_t* vg_ = Vh + (size_t)(t) * 64 * LDV; LAS unsigned char* sb_ = lds + V_OFF + (vs) * SHM_V; \
;     _Pragma("unroll") for (int i_ = 0; i_ < 2; ++i_) __builtin_amdgcn_global_load_lds((const unsigned*)(vg_ + vgo[i_]), (LAS unsigned*)(sb_ + (2 * wid + i_) * 1024), 16, 0, 0); } while (0)
; #define ATT_SEG(t) do { if constexpr (MODE != 0) { if (((t) == tL && tL > 0) || (t) == tR) { const float f_ = (t) == tR ? fR : fL; l_reg *= f_; \
;     _Pragma("unroll") for (int d = 0; d < 4; ++d) _Pragma("unroll") for (int r = 0; r < 16; ++r) o[d][r] *= f_; } } } while (0)
; #define ATT_BIAS(P, t, half) do { if constexpr (MODE != 0) { if ((t) >= tL && (t) < tR) { const LAS float* bp_ = bt + ((t) * 64 + (half) * 32 - qpos + 224 + 4 * hi);     \
;     _Pragma("unroll") for (int r = 0; r < 16; ++r) P[r] += bp_[(r & 3) + 8 * (r >> 2)]; } } } while (0)
; #define ATT_TOP(N) do { asm volatile("s_waitcnt vmcnt(%0)" :: "n"(N) : "memory"); __builtin_amdgcn_s_barrier(); asm volatile("" ::: "memory"); } while (0)
; template <int DQK, int MODE, int LDQ, int LDK, int LDV> ...
;     ...
;     f32x16 pA, pB; bf16x8 pa0, pa1;
;     int v0 = 0, v1 = 1, v2 = 2;
;     ATT_TOP(NKP + 2);
;     { bf16x8 kf[NDA]; k_reads<DQK, 0, NDA>(kf, lds, 0, r32, hi); ATT_LGKM0(); qk_mma<0, NDA>(pA, kf, qr);
;       if constexpr (ND0 > NDA) { bf16x8 kg[ND0 - NDA]; k_reads<DQK, NDA, ND0>(kg, lds, 0, r32, hi); ATT_LGKM0(); qk_mma<NDA, ND0>(pA, kg, qr); }
;       ATT_BIAS(pA, 0, 0); }
;     if (wid >= 4) __builtin_amdgcn_s_setprio(1);
;     for (int j = 0; j < NT; ++j) {
;         if (j + 2 < NT) ATT_TOP(NKP + 2); else ATT_TOP(0);
;         if (j + 3 < NT) ATT_DMA_K(j + 3);
;         if (j + 2 < NT) ATT_DMA_V(j + 2, v2);
;         ATT_SEG(j); SBAR();
;         ATT_STEP(pA, pB, 0, v0, true, 1, j);
;         ATT_STEP(pB, pA, 1, v0, (j + 1 < NT), 0, j + 1);
;         { const int t_ = v0; v0 = v1; v1 = v2; v2 = t_; }
;     }
	ds_read_b128 v[230:233], v252 offset:12416
	ds_read_b128 v[234:237], v253 offset:12416
	ds_read_b128 v[238:241], v250 offset:12544
	ds_read_b128 v[242:245], v251 offset:12544
	ds_read_b128 v[246:249], v252 offset:12544
	ds_read_b128 v[250:253], v253 offset:12544
	s_setprio 2
	v_mfma_f32_32x32x16_bf16 v[48:63], v[64:67], v[198:201], v[48:63]
	v_mfma_f32_32x32x16_bf16 v[32:47], v[64:67], v[206:209], v[32:47]
	v_mfma_f32_32x32x16_bf16 v[16:31], v[64:67], v[214:217], v[16:31]
	v_mfma_f32_32x32x16_bf16 v[0:15], v[64:67], v[222:225], v[0:15]
	v_mfma_f32_32x32x16_bf16 v[48:63], v[68:71], v[202:205], v[48:63]
	v_mfma_f32_32x32x16_bf16 v[32:47], v[68:71], v[210:213], v[32:47]
	v_mfma_f32_32x32x16_bf16 v[16:31], v[68:71], v[218:221], v[16:31]
	v_mfma_f32_32x32x16_bf16 v[0:15], v[68:71], v[226:229], v[0:15]
	s_waitcnt lgkmcnt(0)
	v_mfma_f32_32x32x16_bf16 v[64:79], v[174:177], v[80:83], 0
	v_mfma_f32_32x32x16_bf16 v[64:79], v[178:181], v[84:87], v[64:79]
	v_mfma_f32_32x32x16_bf16 v[64:79], v[182:185], v[88:91], v[64:79]
	v_mfma_f32_32x32x16_bf16 v[64:79], v[186:189], v[92:95], v[64:79]
	v_mfma_f32_32x32x16_bf16 v[64:79], v[190:193], v[96:99], v[64:79]
	v_mfma_f32_32x32x16_bf16 v[64:79], v[194:197], v[100:103], v[64:79]
	v_mfma_f32_32x32x16_bf16 v[64:79], v[230:233], v[104:107], v[64:79]
	v_mfma_f32_32x32x16_bf16 v[64:79], v[234:237], v[108:111], v[64:79]
	v_mfma_f32_32x32x16_bf16 v[64:79], v[238:241], v[112:115], v[64:79]
	v_mfma_f32_32x32x16_bf16 v[64:79], v[242:245], v[116:119], v[64:79]
	v_mfma_f32_32x32x16_bf16 v[64:79], v[246:249], v[120:123], v[64:79]
	v_mfma_f32_32x32x16_bf16 v[64:79], v[250:253], v[124:127], v[64:79]
	s_setprio 0
	s_add_i32 s4, s43, -2
	s_and_b32 s4, s4, 3
	s_mulk_i32 s4, 0x6000
	v_add_u32_e32 v246, s4, v158
	v_add_u32_e32 v250, v246, v151
	v_add_u32_e32 v251, v246, v149
	v_add_u32_e32 v252, v246, v148
	v_add_u32_e32 v253, v246, v147
	ds_read_b128 v[190:193], v250 offset:128
	ds_read_b128 v[194:197], v251 offset:128
	ds_read_b128 v[174:177], v250
	ds_read_b128 v[178:181], v251
	ds_read_b128 v[182:185], v252
	ds_read_b128 v[186:189], v253
	ds_read_b64_tr_b16 v[198:199], v254 offset:0x2000
	ds_read_b64_tr_b16 v[200:201], v254 offset:0x2800
	ds_read_b64_tr_b16 v[202:203], v254 offset:0x3000
	ds_read_b64_tr_b16 v[204:205], v254 offset:0x3800
	ds_read_b64_tr_b16 v[206:207], v254 offset:0x2200
	ds_read_b64_tr_b16 v[208:209], v254 offset:0x2a00
	ds_read_b64_tr_b16 v[210:211], v254 offset:0x3200
	ds_read_b64_tr_b16 v[212:213], v254 offset:0x3a00
	ds_read_b64_tr_b16 v[214:215], v254 offset:0x2400
	ds_read_b64_tr_b16 v[216:217], v254 offset:0x2c00
	ds_read_b64_tr_b16 v[218:219], v254 offset:0x3400
	ds_read_b64_tr_b16 v[220:221], v254 offset:0x3c00
	ds_read_b64_tr_b16 v[222:223], v254 offset:0x2600
	ds_read_b64_tr_b16 v[224:225], v254 offset:0x2e00
	ds_read_b64_tr_b16 v[226:227], v254 offset:0x3600
	ds_read_b64_tr_b16 v[228:229], v254 offset:0x3e00
	s_setprio 1
	v_exp_f32_e32 v64, v64
	v_exp_f32_e32 v65, v65
	v_exp_f32_e32 v66, v66
	v_exp_f32_e32 v67, v67
	v_exp_f32_e32 v68, v68
	v_exp_f32_e32 v69, v69
	v_add_f32_e32 v230, v65, v64
	v_exp_f32_e32 v70, v70
	v_add_f32_e32 v230, v66, v230
	v_exp_f32_e32 v71, v71
	v_add_f32_e32 v230, v67, v230
	v_exp_f32_e32 v72, v72
	v_add_f32_e32 v230, v68, v230
	v_exp_f32_e32 v73, v73
	v_add_f32_e32 v230, v69, v230
	v_exp_f32_e32 v74, v74
	v_add_f32_e32 v230, v70, v230
	v_exp_f32_e32 v75, v75
	v_add_f32_e32 v230, v71, v230
	v_exp_f32_e32 v76, v76
	v_add_f32_e32 v230, v72, v230
	v_exp_f32_e32 v77, v77
	v_add_f32_e32 v230, v73, v230
	v_exp_f32_e32 v78, v78
	v_add_f32_e32 v230, v74, v230
	v_exp_f32_e32 v79, v79
	v_add_f32_e32 v230, v75, v230
	v_add_f32_e32 v230, v76, v230
	v_add_f32_e32 v230, v77, v230
	v_add_f32_e32 v230, v78, v230
	v_add_f32_e32 v230, v79, v230
	v_add_f32_e32 v173, v173, v230
	v_cvt_pk_bf16_f32 v64, v64, v65
	v_cvt_pk_bf16_f32 v65, v66, v67
	v_cvt_pk_bf16_f32 v66, v68, v69
	v_cvt_pk_bf16_f32 v67, v70, v71
	v_cvt_pk_bf16_f32 v68, v72, v73
	v_cvt_pk_bf16_f32 v69, v74, v75
	v_cvt_pk_bf16_f32 v70, v76, v77
	v_cvt_pk_bf16_f32 v71, v78, v79
	s_waitcnt lgkmcnt(0)
	ds_read_b128 v[230:233], v252 offset:128
	ds_read_b128 v[234:237], v253 offset:128
	ds_read_b128 v[238:241], v250 offset:256
	ds_read_b128 v[242:245], v251 offset:256
	ds_read_b128 v[246:249], v252 offset:256
	ds_read_b128 v[250:253], v253 offset:256
	s_setprio 2
	v_mfma_f32_32x32x16_bf16 v[48:63], v[64:67], v[198:201], v[48:63]
	v_mfma_f32_32x32x16_bf16 v[32:47], v[64:67], v[206:209], v[32:47]
	v_mfma_f32_32x32x16_bf16 v[16:31], v[64:67], v[214:217], v[16:31]
	v_mfma_f32_32x32x16_bf16 v[0:15], v[64:67], v[222:225], v[0:15]
	v_mfma_f32_32x32x16_bf16 v[48:63], v[68:71], v[202:205], v[48:63]
	v_mfma_f32_32x32x16_bf16 v[32:47], v[68:71], v[210:213], v[32:47]
	v_mfma_f32_32x32x16_bf16 v[16:31], v[68:71], v[218:221], v[16:31]
	v_mfma_f32_32x32x16_bf16 v[0:15], v[68:71], v[226:229], v[0:15]
	s_waitcnt lgkmcnt(0)
	v_mfma_f32_32x32x16_bf16 v[64:79], v[174:177], v[80:83], 0
	v_mfma_f32_32x32x16_bf16 v[64:79], v[178:181], v[84:87], v[64:79]
	v_mfma_f32_32x32x16_bf16 v[64:79], v[182:185], v[88:91], v[64:79]
	v_mfma_f32_32x32x16_bf16 v[64:79], v[186:189], v[92:95], v[64:79]
	v_mfma_f32_32x32x16_bf16 v[64:79], v[190:193], v[96:99], v[64:79]
	v_mfma_f32_32x32x16_bf16 v[64:79], v[194:197], v[100:103], v[64:79]
	v_mfma_f32_32x32x16_bf16 v[64:79], v[230:233], v[104:107], v[64:79]
	v_mfma_f32_32x32x16_bf16 v[64:79], v[234:237], v[108:111], v[64:79]
	v_mfma_f32_32x32x16_bf16 v[64:79], v[238:241], v[112:115], v[64:79]
	v_mfma_f32_32x32x16_bf16 v[64:79], v[242:245], v[116:119], v[64:79]
	v_mfma_f32_32x32x16_bf16 v[64:79], v[246:249], v[120:123], v[64:79]
	v_mfma_f32_32x32x16_bf16 v[64:79], v[250:253], v[124:127], v[64:79]
	s_add_i32 s43, s43, 1
	v_add_u32_e32 v136, s36, v136
	v_add_u32_e32 v138, s36, v138
	v_add_u32_e32 v140, s36, v140
	v_add_u32_e32 v142, s38, v142
	v_add_u32_e32 v144, s38, v144
	s_cmp_eq_u32 s43, 64
	s_mov_b32 s4, s0
	s_cbranch_scc0 .LBB0_1982
